# loop-edge edit: P3/P9 tile-loop back edge folded into one conditional branch
# baseline (speedup 1.0000x reference)
.LBB0_574:
	s_add_u32 s40, s40, 0x20000
	s_addc_u32 s41, s41, 0
	s_add_i32 s72, s72, -1
	s_cmp_eq_u32 s28, s77
	v_add_u32_e32 v191, 0xffffff00, v191
	s_waitcnt lgkmcnt(0)
	s_barrier
	s_mov_b32 s48, s77
	s_cbranch_scc0 .LBB0_548
	s_branch .LBB0_578

.LBB0_1356:
	s_cmp_eq_u32 s52, s53
	s_waitcnt lgkmcnt(0)
	s_barrier
	s_mov_b32 s54, s53
	s_cbranch_scc0 .LBB0_1335
	s_branch .LBB0_1359
